# up-GEMM epilogue stores use the nt cache policy (FF is 268 MB, read once by the next phase)
# speedup vs baseline: 1.0081x; 1.0056x over previous
.LBB0_1091:
	s_add_u32 s2, s60, 0xfff80080
	s_addc_u32 s3, s61, -1
	s_add_i32 s70, 0, 0x10000
	v_add_u32_e32 v116, s70, v215
	ds_read_b128 v[100:103], v116
	ds_read_b128 v[108:111], v116 offset:1024
	ds_read_b128 v[112:115], v116 offset:2048
	ds_read_b128 v[116:119], v116 offset:3072
	s_cmp_eq_u32 s69, 28
	s_cselect_b32 s21, s18, s3
	s_cselect_b32 s20, s19, s2
	s_cselect_b32 s3, s34, s51
	s_cselect_b32 s2, s35, s49
	v_lshl_add_u64 v[186:187], s[60:61], 0, v[168:169]
	s_add_i32 m0, s59, 0xc000
	ds_read_b128 v[120:123], v217
	ds_read_b128 v[124:127], v217 offset:1024
	ds_read_b128 v[128:131], v217 offset:2048
	ds_read_b128 v[132:135], v217 offset:3072
	ds_read_b128 v[170:173], v217 offset:4096
	ds_read_b128 v[174:177], v217 offset:5120
	ds_read_b128 v[178:181], v217 offset:6144
	ds_read_b128 v[182:185], v217 offset:7168
	global_load_lds_dwordx4 v[186:187], off
	v_lshl_add_u64 v[186:187], s[60:61], 0, v[166:167]
	s_add_i32 m0, s59, 0xe000
	s_nop 0
	global_load_lds_dwordx4 v[186:187], off
	s_waitcnt lgkmcnt(8)
	s_barrier
	s_waitcnt lgkmcnt(0)
	s_setprio 1
	s_waitcnt lgkmcnt(0)
	v_mfma_f32_16x16x32_bf16 v[156:159], v[100:103], v[120:123], v[156:159]
	v_mfma_f32_16x16x32_bf16 v[152:155], v[112:115], v[120:123], v[152:155]
	v_mfma_f32_16x16x32_bf16 v[140:143], v[100:103], v[128:131], v[140:143]
	v_mfma_f32_16x16x32_bf16 v[136:139], v[112:115], v[128:131], v[136:139]
	v_mfma_f32_16x16x32_bf16 v[92:95], v[100:103], v[170:173], v[92:95]
	v_mfma_f32_16x16x32_bf16 v[88:91], v[112:115], v[170:173], v[88:91]
	v_mfma_f32_16x16x32_bf16 v[76:79], v[100:103], v[178:181], v[76:79]
	v_mfma_f32_16x16x32_bf16 v[72:75], v[112:115], v[178:181], v[72:75]
	v_mfma_f32_16x16x32_bf16 v[156:159], v[108:111], v[124:127], v[156:159]
	v_mfma_f32_16x16x32_bf16 v[152:155], v[116:119], v[124:127], v[152:155]
	v_mfma_f32_16x16x32_bf16 v[140:143], v[108:111], v[132:135], v[140:143]
	v_mfma_f32_16x16x32_bf16 v[136:139], v[116:119], v[132:135], v[136:139]
	v_mfma_f32_16x16x32_bf16 v[92:95], v[108:111], v[174:177], v[92:95]
	v_mfma_f32_16x16x32_bf16 v[88:91], v[116:119], v[174:177], v[88:91]
	v_mfma_f32_16x16x32_bf16 v[76:79], v[108:111], v[182:185], v[76:79]
	v_mfma_f32_16x16x32_bf16 v[72:75], v[116:119], v[182:185], v[72:75]
	s_setprio 0
	s_barrier
	s_add_i32 s74, 0, 0x14000
	v_add_u32_e32 v190, s74, v215
	s_add_i32 s70, s70, s53
	ds_read_b128 v[186:189], v190
	ds_read_b128 v[202:205], v190 offset:1024
	ds_read_b128 v[206:209], v190 offset:2048
	ds_read_b128 v[210:213], v190 offset:3072
	v_lshl_add_u64 v[190:191], s[2:3], 0, v[194:195]
	s_mov_b32 m0, s70
	v_lshl_add_u64 v[222:223], s[2:3], 0, v[164:165]
	global_load_lds_dwordx4 v[190:191], off
	s_add_i32 m0, s70, 0x2000
	s_nop 0
	global_load_lds_dwordx4 v[222:223], off
	s_barrier
	s_waitcnt lgkmcnt(0)
	s_setprio 1
	s_waitcnt lgkmcnt(0)
	v_mfma_f32_16x16x32_bf16 v[148:151], v[186:189], v[120:123], v[148:151]
	v_mfma_f32_16x16x32_bf16 v[104:107], v[186:189], v[128:131], v[104:107]
	v_mfma_f32_16x16x32_bf16 v[96:99], v[206:209], v[128:131], v[96:99]
	v_mfma_f32_16x16x32_bf16 v[84:87], v[186:189], v[170:173], v[84:87]
	v_mfma_f32_16x16x32_bf16 v[80:83], v[206:209], v[170:173], v[80:83]
	v_mfma_f32_16x16x32_bf16 v[68:71], v[186:189], v[178:181], v[68:71]
	v_mfma_f32_16x16x32_bf16 v[64:67], v[206:209], v[178:181], v[64:67]
	v_mfma_f32_16x16x32_bf16 v[148:151], v[202:205], v[124:127], v[148:151]
	v_mfma_f32_16x16x32_bf16 v[120:123], v[206:209], v[120:123], v[144:147]
	v_mfma_f32_16x16x32_bf16 v[104:107], v[202:205], v[132:135], v[104:107]
	v_mfma_f32_16x16x32_bf16 v[96:99], v[210:213], v[132:135], v[96:99]
	v_mfma_f32_16x16x32_bf16 v[84:87], v[202:205], v[174:177], v[84:87]
	v_mfma_f32_16x16x32_bf16 v[80:83], v[210:213], v[174:177], v[80:83]
	v_mfma_f32_16x16x32_bf16 v[68:71], v[202:205], v[182:185], v[68:71]
	v_mfma_f32_16x16x32_bf16 v[64:67], v[210:213], v[182:185], v[64:67]
	v_mfma_f32_16x16x32_bf16 v[120:123], v[210:213], v[124:127], v[120:123]
	s_setprio 0
	s_mov_b32 m0, s59
	v_lshl_add_u64 v[224:225], s[20:21], 0, v[160:161]
	s_barrier
	ds_read_b128 v[124:127], v217 offset:16384
	ds_read_b128 v[128:131], v217 offset:17408
	ds_read_b128 v[132:135], v217 offset:18432
	ds_read_b128 v[144:147], v217 offset:19456
	ds_read_b128 v[170:173], v217 offset:20480
	ds_read_b128 v[174:177], v217 offset:21504
	ds_read_b128 v[178:181], v217 offset:22528
	ds_read_b128 v[182:185], v217 offset:23552
	global_load_lds_dwordx4 v[224:225], off
	v_lshl_add_u64 v[226:227], s[20:21], 0, v[162:163]
	s_mov_b32 m0, s62
	s_nop 0
	global_load_lds_dwordx4 v[226:227], off
	s_barrier
	s_waitcnt lgkmcnt(0)
	s_setprio 1
	s_waitcnt lgkmcnt(0)
	v_mfma_f32_16x16x32_bf16 v[60:63], v[100:103], v[124:127], v[60:63]
	v_mfma_f32_16x16x32_bf16 v[56:59], v[112:115], v[124:127], v[56:59]
	v_mfma_f32_16x16x32_bf16 v[44:47], v[100:103], v[132:135], v[44:47]
	v_mfma_f32_16x16x32_bf16 v[40:43], v[112:115], v[132:135], v[40:43]
	v_mfma_f32_16x16x32_bf16 v[28:31], v[100:103], v[170:173], v[28:31]
	v_mfma_f32_16x16x32_bf16 v[24:27], v[112:115], v[170:173], v[24:27]
	v_mfma_f32_16x16x32_bf16 v[12:15], v[100:103], v[178:181], v[12:15]
	v_mfma_f32_16x16x32_bf16 v[8:11], v[112:115], v[178:181], v[8:11]
	v_mfma_f32_16x16x32_bf16 v[60:63], v[108:111], v[128:131], v[60:63]
	v_mfma_f32_16x16x32_bf16 v[56:59], v[116:119], v[128:131], v[56:59]
	v_mfma_f32_16x16x32_bf16 v[44:47], v[108:111], v[144:147], v[44:47]
	v_mfma_f32_16x16x32_bf16 v[40:43], v[116:119], v[144:147], v[40:43]
	v_mfma_f32_16x16x32_bf16 v[28:31], v[108:111], v[174:177], v[28:31]
	v_mfma_f32_16x16x32_bf16 v[24:27], v[116:119], v[174:177], v[24:27]
	v_mfma_f32_16x16x32_bf16 v[12:15], v[108:111], v[182:185], v[12:15]
	v_mfma_f32_16x16x32_bf16 v[8:11], v[116:119], v[182:185], v[8:11]
	s_setprio 0
	s_barrier
	s_add_u32 s70, s2, 0x80000
	s_addc_u32 s71, s3, 0
	s_add_i32 s74, s74, s53
	v_lshl_add_u64 v[100:101], s[70:71], 0, v[194:195]
	s_mov_b32 m0, s74
	s_nop 0
	global_load_lds_dwordx4 v[100:101], off
	v_lshl_add_u64 v[100:101], s[70:71], 0, v[164:165]
	s_add_i32 m0, s74, 0x2000
	s_nop 0
	global_load_lds_dwordx4 v[100:101], off
	s_waitcnt vmcnt(6)
	s_barrier
	s_setprio 1
	v_mfma_f32_16x16x32_bf16 v[52:55], v[186:189], v[124:127], v[52:55]
	v_mfma_f32_16x16x32_bf16 v[48:51], v[206:209], v[124:127], v[48:51]
	v_mfma_f32_16x16x32_bf16 v[36:39], v[186:189], v[132:135], v[36:39]
	v_mfma_f32_16x16x32_bf16 v[32:35], v[206:209], v[132:135], v[32:35]
	v_mfma_f32_16x16x32_bf16 v[20:23], v[186:189], v[170:173], v[20:23]
	v_mfma_f32_16x16x32_bf16 v[16:19], v[206:209], v[170:173], v[16:19]
	v_mfma_f32_16x16x32_bf16 v[4:7], v[186:189], v[178:181], v[4:7]
	v_mfma_f32_16x16x32_bf16 v[0:3], v[206:209], v[178:181], v[0:3]
	v_mfma_f32_16x16x32_bf16 v[52:55], v[202:205], v[128:131], v[52:55]
	v_mfma_f32_16x16x32_bf16 v[48:51], v[210:213], v[128:131], v[48:51]
	v_mfma_f32_16x16x32_bf16 v[36:39], v[202:205], v[144:147], v[36:39]
	v_mfma_f32_16x16x32_bf16 v[32:35], v[210:213], v[144:147], v[32:35]
	v_mfma_f32_16x16x32_bf16 v[20:23], v[202:205], v[174:177], v[20:23]
	v_mfma_f32_16x16x32_bf16 v[16:19], v[210:213], v[174:177], v[16:19]
	v_mfma_f32_16x16x32_bf16 v[4:7], v[202:205], v[182:185], v[4:7]
	v_mfma_f32_16x16x32_bf16 v[0:3], v[210:213], v[182:185], v[0:3]
	s_setprio 0
	s_add_i32 s70, 0, 0x18000
	v_add_u32_e32 v116, s70, v215
	s_barrier
	ds_read_b128 v[100:103], v116
	ds_read_b128 v[108:111], v116 offset:1024
	ds_read_b128 v[112:115], v116 offset:2048
	ds_read_b128 v[116:119], v116 offset:3072
	s_add_u32 s20, s20, 0x80000
	s_addc_u32 s21, s21, 0
	s_mov_b32 m0, s63
	v_lshl_add_u64 v[144:145], s[20:21], 0, v[160:161]
	ds_read_b128 v[124:127], v217 offset:32768
	ds_read_b128 v[128:131], v217 offset:33792
	ds_read_b128 v[132:135], v217 offset:34816
	ds_read_b128 v[170:173], v217 offset:35840
	ds_read_b128 v[174:177], v217 offset:36864
	ds_read_b128 v[178:181], v217 offset:37888
	ds_read_b128 v[182:185], v217 offset:38912
	ds_read_b128 v[186:189], v217 offset:39936
	global_load_lds_dwordx4 v[144:145], off
	v_lshl_add_u64 v[144:145], s[20:21], 0, v[162:163]
	s_mov_b32 m0, s64
	s_nop 0
	global_load_lds_dwordx4 v[144:145], off
	s_waitcnt lgkmcnt(8)
	s_barrier
	s_waitcnt lgkmcnt(0)
	s_setprio 1
	s_waitcnt lgkmcnt(0)
	v_mfma_f32_16x16x32_bf16 v[144:147], v[100:103], v[124:127], v[156:159]
	v_mfma_f32_16x16x32_bf16 v[156:159], v[108:111], v[128:131], v[144:147]
	v_mfma_f32_16x16x32_bf16 v[144:147], v[112:115], v[124:127], v[152:155]
	v_mfma_f32_16x16x32_bf16 v[140:143], v[100:103], v[132:135], v[140:143]
	v_mfma_f32_16x16x32_bf16 v[136:139], v[112:115], v[132:135], v[136:139]
	v_mfma_f32_16x16x32_bf16 v[92:95], v[100:103], v[174:177], v[92:95]
	v_mfma_f32_16x16x32_bf16 v[88:91], v[112:115], v[174:177], v[88:91]
	v_mfma_f32_16x16x32_bf16 v[76:79], v[100:103], v[182:185], v[76:79]
	v_mfma_f32_16x16x32_bf16 v[72:75], v[112:115], v[182:185], v[72:75]
	v_mfma_f32_16x16x32_bf16 v[152:155], v[116:119], v[128:131], v[144:147]
	v_mfma_f32_16x16x32_bf16 v[140:143], v[108:111], v[170:173], v[140:143]
	v_mfma_f32_16x16x32_bf16 v[136:139], v[116:119], v[170:173], v[136:139]
	v_mfma_f32_16x16x32_bf16 v[92:95], v[108:111], v[178:181], v[92:95]
	v_mfma_f32_16x16x32_bf16 v[88:91], v[116:119], v[178:181], v[88:91]
	v_mfma_f32_16x16x32_bf16 v[76:79], v[108:111], v[186:189], v[76:79]
	v_mfma_f32_16x16x32_bf16 v[72:75], v[116:119], v[186:189], v[72:75]
	s_setprio 0
	s_barrier
	s_add_i32 s20, 0, 0x1c000
	v_add_u32_e32 v144, s20, v215
	s_add_i32 s21, s70, s53
	ds_read_b128 v[202:205], v144
	ds_read_b128 v[206:209], v144 offset:1024
	ds_read_b128 v[210:213], v144 offset:2048
	ds_read_b128 v[218:221], v144 offset:3072
	v_lshl_add_u64 v[144:145], v[190:191], 0, s[26:27]
	s_mov_b32 m0, s21
	s_nop 0
	global_load_lds_dwordx4 v[144:145], off
	v_lshl_add_u64 v[144:145], v[222:223], 0, s[26:27]
	s_add_i32 m0, s21, 0x2000
	s_nop 0
	global_load_lds_dwordx4 v[144:145], off
	s_barrier
	s_waitcnt lgkmcnt(0)
	s_setprio 1
	s_waitcnt lgkmcnt(0)
	v_mfma_f32_16x16x32_bf16 v[144:147], v[202:205], v[124:127], v[148:151]
	v_mfma_f32_16x16x32_bf16 v[120:123], v[210:213], v[124:127], v[120:123]
	v_mfma_f32_16x16x32_bf16 v[104:107], v[202:205], v[132:135], v[104:107]
	v_mfma_f32_16x16x32_bf16 v[96:99], v[210:213], v[132:135], v[96:99]
	v_mfma_f32_16x16x32_bf16 v[84:87], v[202:205], v[174:177], v[84:87]
	v_mfma_f32_16x16x32_bf16 v[80:83], v[210:213], v[174:177], v[80:83]
	v_mfma_f32_16x16x32_bf16 v[68:71], v[202:205], v[182:185], v[68:71]
	v_mfma_f32_16x16x32_bf16 v[64:67], v[210:213], v[182:185], v[64:67]
	v_mfma_f32_16x16x32_bf16 v[148:151], v[206:209], v[128:131], v[144:147]
	v_mfma_f32_16x16x32_bf16 v[144:147], v[218:221], v[128:131], v[120:123]
	v_mfma_f32_16x16x32_bf16 v[104:107], v[206:209], v[170:173], v[104:107]
	v_mfma_f32_16x16x32_bf16 v[96:99], v[218:221], v[170:173], v[96:99]
	v_mfma_f32_16x16x32_bf16 v[84:87], v[206:209], v[178:181], v[84:87]
	v_mfma_f32_16x16x32_bf16 v[80:83], v[218:221], v[178:181], v[80:83]
	v_mfma_f32_16x16x32_bf16 v[68:71], v[206:209], v[186:189], v[68:71]
	v_mfma_f32_16x16x32_bf16 v[64:67], v[218:221], v[186:189], v[64:67]
	s_setprio 0
	s_mov_b32 m0, s16
	v_lshl_add_u64 v[186:187], v[224:225], 0, s[26:27]
	s_barrier
	ds_read_b128 v[120:123], v217 offset:49152
	ds_read_b128 v[124:127], v217 offset:50176
	ds_read_b128 v[128:131], v217 offset:51200
	ds_read_b128 v[132:135], v217 offset:52224
	ds_read_b128 v[170:173], v217 offset:53248
	ds_read_b128 v[174:177], v217 offset:54272
	ds_read_b128 v[178:181], v217 offset:55296
	ds_read_b128 v[182:185], v217 offset:56320
	global_load_lds_dwordx4 v[186:187], off
	v_lshl_add_u64 v[186:187], v[226:227], 0, s[26:27]
	s_mov_b32 m0, s65
	s_nop 0
	global_load_lds_dwordx4 v[186:187], off
	s_barrier
	s_waitcnt lgkmcnt(0)
	s_setprio 1
	s_waitcnt lgkmcnt(0)
	v_mfma_f32_16x16x32_bf16 v[60:63], v[100:103], v[120:123], v[60:63]
	v_mfma_f32_16x16x32_bf16 v[56:59], v[112:115], v[120:123], v[56:59]
	v_mfma_f32_16x16x32_bf16 v[44:47], v[100:103], v[128:131], v[44:47]
	v_mfma_f32_16x16x32_bf16 v[40:43], v[112:115], v[128:131], v[40:43]
	v_mfma_f32_16x16x32_bf16 v[28:31], v[100:103], v[170:173], v[28:31]
	v_mfma_f32_16x16x32_bf16 v[24:27], v[112:115], v[170:173], v[24:27]
	v_mfma_f32_16x16x32_bf16 v[12:15], v[100:103], v[178:181], v[12:15]
	v_mfma_f32_16x16x32_bf16 v[8:11], v[112:115], v[178:181], v[8:11]
	v_mfma_f32_16x16x32_bf16 v[60:63], v[108:111], v[124:127], v[60:63]
	v_mfma_f32_16x16x32_bf16 v[56:59], v[116:119], v[124:127], v[56:59]
	v_mfma_f32_16x16x32_bf16 v[44:47], v[108:111], v[132:135], v[44:47]
	v_mfma_f32_16x16x32_bf16 v[40:43], v[116:119], v[132:135], v[40:43]
	v_mfma_f32_16x16x32_bf16 v[28:31], v[108:111], v[174:177], v[28:31]
	v_mfma_f32_16x16x32_bf16 v[24:27], v[116:119], v[174:177], v[24:27]
	v_mfma_f32_16x16x32_bf16 v[12:15], v[108:111], v[182:185], v[12:15]
	v_mfma_f32_16x16x32_bf16 v[8:11], v[116:119], v[182:185], v[8:11]
	s_setprio 0
	s_barrier
	s_add_u32 s2, s2, 0x80080
	s_addc_u32 s3, s3, 0
	s_add_i32 s20, s20, s53
	v_lshl_add_u64 v[100:101], s[2:3], 0, v[194:195]
	s_mov_b32 m0, s20
	s_nop 0
	global_load_lds_dwordx4 v[100:101], off
	v_lshl_add_u64 v[100:101], s[2:3], 0, v[164:165]
	s_add_i32 m0, s20, 0x2000
	s_nop 0
	global_load_lds_dwordx4 v[100:101], off
	s_waitcnt vmcnt(6)
	s_barrier
	s_setprio 1
	v_mfma_f32_16x16x32_bf16 v[52:55], v[202:205], v[120:123], v[52:55]
	v_mfma_f32_16x16x32_bf16 v[48:51], v[210:213], v[120:123], v[48:51]
	v_mfma_f32_16x16x32_bf16 v[36:39], v[202:205], v[128:131], v[36:39]
	v_mfma_f32_16x16x32_bf16 v[32:35], v[210:213], v[128:131], v[32:35]
	v_mfma_f32_16x16x32_bf16 v[20:23], v[202:205], v[170:173], v[20:23]
	v_mfma_f32_16x16x32_bf16 v[16:19], v[210:213], v[170:173], v[16:19]
	v_mfma_f32_16x16x32_bf16 v[4:7], v[202:205], v[178:181], v[4:7]
	v_mfma_f32_16x16x32_bf16 v[0:3], v[210:213], v[178:181], v[0:3]
	v_mfma_f32_16x16x32_bf16 v[52:55], v[206:209], v[124:127], v[52:55]
	v_mfma_f32_16x16x32_bf16 v[48:51], v[218:221], v[124:127], v[48:51]
	v_mfma_f32_16x16x32_bf16 v[36:39], v[206:209], v[132:135], v[36:39]
	v_mfma_f32_16x16x32_bf16 v[32:35], v[218:221], v[132:135], v[32:35]
	v_mfma_f32_16x16x32_bf16 v[20:23], v[206:209], v[174:177], v[20:23]
	v_mfma_f32_16x16x32_bf16 v[16:19], v[218:221], v[174:177], v[16:19]
	v_mfma_f32_16x16x32_bf16 v[4:7], v[206:209], v[182:185], v[4:7]
	v_mfma_f32_16x16x32_bf16 v[0:3], v[218:221], v[182:185], v[0:3]
	s_setprio 0
	s_add_i32 s69, s69, 2
	s_add_u32 s49, s49, 0x100
	s_addc_u32 s51, s51, 0
	s_add_u32 s60, s60, 0x100
	s_addc_u32 s61, s61, 0
	s_cmp_gt_u32 s69, 29
	s_barrier
	s_cbranch_scc0 .LBB0_1091
	v_lshl_or_b32 v174, s68, 8, v216
	v_ashrrev_i32_e32 v175, 31, v174
	v_lshlrev_b64 v[100:101], 2, v[174:175]
	v_lshl_add_u32 v210, s58, 8, v214
	v_lshl_add_u64 v[102:103], s[44:45], 0, v[100:101]
	v_lshl_add_u64 v[100:101], s[46:47], 0, v[100:101]
	global_load_dwordx4 v[128:131], v[102:103], off offset:16
	global_load_dwordx4 v[132:135], v[102:103], off
	global_load_dwordx4 v[120:123], v[100:101], off offset:16
	global_load_dwordx4 v[124:127], v[100:101], off
	v_or_b32_e32 v100, 0x80, v174
	v_ashrrev_i32_e32 v101, 31, v100
	v_add_u32_e32 v206, 16, v210
	v_add_u32_e32 v202, 32, v210
	v_add_u32_e32 v188, 48, v210
	v_add_u32_e32 v184, 0x80, v210
	v_add_u32_e32 v180, 0x90, v210
	v_add_u32_e32 v178, 0xa0, v210
	v_lshlrev_b64 v[100:101], 2, v[100:101]
	v_ashrrev_i32_e32 v211, 31, v210
	v_ashrrev_i32_e32 v207, 31, v206
	v_ashrrev_i32_e32 v203, 31, v202
	v_ashrrev_i32_e32 v189, 31, v188
	v_ashrrev_i32_e32 v185, 31, v184
	v_ashrrev_i32_e32 v181, 31, v180
	v_ashrrev_i32_e32 v179, 31, v178
	v_add_u32_e32 v172, 0xb0, v210
	v_lshl_add_u64 v[102:103], s[44:45], 0, v[100:101]
	v_lshl_add_u64 v[108:109], s[46:47], 0, v[100:101]
	v_lshl_add_u64 v[170:171], v[210:211], 3, s[42:43]
	v_lshl_add_u64 v[208:209], v[206:207], 3, s[42:43]
	v_lshl_add_u64 v[204:205], v[202:203], 3, s[42:43]
	v_lshl_add_u64 v[190:191], v[188:189], 3, s[42:43]
	v_lshl_add_u64 v[186:187], v[184:185], 3, s[42:43]
	v_lshl_add_u64 v[182:183], v[180:181], 3, s[42:43]
	v_lshl_add_u64 v[176:177], v[178:179], 3, s[42:43]
	v_ashrrev_i32_e32 v173, 31, v172
	global_load_dwordx4 v[112:115], v[102:103], off offset:16
	global_load_dwordx4 v[116:119], v[102:103], off
	s_nop 0
	global_load_dwordx4 v[100:103], v[108:109], off offset:16
	s_nop 0
	global_load_dwordx4 v[108:111], v[108:109], off
	v_lshl_add_u64 v[212:213], v[172:173], 3, s[42:43]
	global_load_dwordx2 v[218:219], v[170:171], off
	s_nop 0
	global_load_dwordx2 v[170:171], v[212:213], off
	s_nop 0
	global_load_dwordx2 v[176:177], v[176:177], off
	s_nop 0
	global_load_dwordx2 v[182:183], v[182:183], off
	s_nop 0
	global_load_dwordx2 v[186:187], v[186:187], off
	s_nop 0
	global_load_dwordx2 v[190:191], v[190:191], off
	s_nop 0
	global_load_dwordx2 v[204:205], v[204:205], off
	s_nop 0
	global_load_dwordx2 v[208:209], v[208:209], off
	v_lshl_add_u64 v[174:175], v[174:175], 1, s[40:41]
	v_lshlrev_b64 v[210:211], 14, v[210:211]
	v_lshl_add_u64 v[210:211], v[174:175], 0, v[210:211]
	s_mov_b32 s68, s48
	s_mov_b32 s58, s50
	s_mov_b64 s[2:3], s[56:57]
	s_mov_b64 s[20:21], s[54:55]
	s_waitcnt vmcnt(0)
	s_nop 0
	v_pk_mul_f32 v[212:213], v[218:219], s[28:29] op_sel_hi:[1,0]
	s_nop 0
	v_fma_f32 v213, -v212, v212, v213
	v_max_f32_e32 v213, 0, v213
	v_add_f32_e32 v213, 0x3727c5ac, v213
	v_cmp_gt_f32_e32 vcc, s13, v213
	v_mul_f32_e32 v218, 0x4b800000, v213
	v_fma_f32 v152, -v128, v212, v152
	v_cndmask_b32_e32 v213, v213, v218, vcc
	v_rsq_f32_e32 v213, v213
	v_fma_f32 v153, -v129, v212, v153
	v_fma_f32 v154, -v130, v212, v154
	v_fma_f32 v156, -v132, v212, v156
	v_mul_f32_e32 v218, 0x45800000, v213
	v_cndmask_b32_e32 v213, v213, v218, vcc
	v_fma_f32 v152, v152, v213, v120
	v_fma_f32 v153, v153, v213, v121
	v_max_f32_e32 v152, 0, v152
	v_fma_f32 v157, -v133, v212, v157
	v_fma_f32 v154, v154, v213, v122
	v_fma_f32 v155, -v131, v212, v155
	v_mul_f32_e32 v218, v152, v152
	v_max_f32_e32 v152, 0, v153
	v_fma_f32 v156, v156, v213, v124
	v_fma_f32 v157, v157, v213, v125
	v_fma_f32 v158, -v134, v212, v158
	v_fma_f32 v159, -v135, v212, v159
	v_fma_f32 v155, v155, v213, v123
	v_mul_f32_e32 v219, v152, v152
	v_max_f32_e32 v152, 0, v154
	v_fma_f32 v144, -v112, v212, v144
	v_fma_f32 v158, v158, v213, v126
	v_fma_f32 v159, v159, v213, v127
	v_max_f32_e32 v156, 0, v156
	v_max_f32_e32 v157, 0, v157
	v_mul_f32_e32 v220, v152, v152
	v_max_f32_e32 v152, 0, v155
	v_fma_f32 v144, v144, v213, v100
	v_fma_f32 v145, -v113, v212, v145
	v_mul_f32_e32 v156, v156, v156
	v_mul_f32_e32 v157, v157, v157
	v_max_f32_e32 v158, 0, v158
	v_max_f32_e32 v159, 0, v159
	v_mul_f32_e32 v155, v152, v152
	v_cvt_pk_bf16_f32 v152, v156, v157
	v_fma_f32 v145, v145, v213, v101
	v_fma_f32 v146, -v114, v212, v146
	v_max_f32_e32 v144, 0, v144
	v_mul_f32_e32 v158, v158, v158
	v_mul_f32_e32 v159, v159, v159
	v_cvt_pk_bf16_f32 v153, v158, v159
	v_cvt_pk_bf16_f32 v154, v218, v219
	v_cvt_pk_bf16_f32 v155, v220, v155
	global_store_dwordx4 v[210:211], v[152:155], off nt
	v_fma_f32 v146, v146, v213, v102
	v_fma_f32 v147, -v115, v212, v147
	v_mul_f32_e32 v152, v144, v144
	v_max_f32_e32 v144, 0, v145
	v_fma_f32 v148, -v116, v212, v148
	v_fma_f32 v149, -v117, v212, v149
	v_fma_f32 v150, -v118, v212, v150
	v_fma_f32 v151, -v119, v212, v151
	v_fma_f32 v147, v147, v213, v103
	v_mul_f32_e32 v153, v144, v144
	v_max_f32_e32 v144, 0, v146
	v_fma_f32 v148, v148, v213, v108
	v_fma_f32 v149, v149, v213, v109
	v_fma_f32 v150, v150, v213, v110
	v_fma_f32 v151, v151, v213, v111
	v_mul_f32_e32 v154, v144, v144
	v_max_f32_e32 v144, 0, v147
	v_max_f32_e32 v148, 0, v148
	v_max_f32_e32 v149, 0, v149
	v_max_f32_e32 v150, 0, v150
	v_max_f32_e32 v151, 0, v151
	v_mul_f32_e32 v147, v144, v144
	v_mul_f32_e32 v148, v148, v148
	v_mul_f32_e32 v149, v149, v149
	v_mul_f32_e32 v150, v150, v150
	v_mul_f32_e32 v151, v151, v151
	v_cvt_pk_bf16_f32 v144, v148, v149
	v_cvt_pk_bf16_f32 v145, v150, v151
	v_cvt_pk_bf16_f32 v146, v152, v153
	v_cvt_pk_bf16_f32 v147, v154, v147
	global_store_dwordx4 v[210:211], v[144:147], off offset:256 nt
	s_nop 1
	v_pk_mul_f32 v[146:147], v[208:209], s[28:29] op_sel_hi:[1,0]
	v_lshlrev_b64 v[144:145], 14, v[206:207]
	v_fma_f32 v147, -v146, v146, v147
	v_max_f32_e32 v147, 0, v147
	v_add_f32_e32 v147, 0x3727c5ac, v147
	v_cmp_gt_f32_e32 vcc, s13, v147
	v_mul_f32_e32 v148, 0x4b800000, v147
	v_fma_f32 v136, -v128, v146, v136
	v_cndmask_b32_e32 v147, v147, v148, vcc
	v_rsq_f32_e32 v147, v147
	v_fma_f32 v137, -v129, v146, v137
	v_fma_f32 v138, -v130, v146, v138
	v_fma_f32 v140, -v132, v146, v140
	v_mul_f32_e32 v148, 0x45800000, v147
	v_cndmask_b32_e32 v147, v147, v148, vcc
	v_fma_f32 v136, v136, v147, v120
	v_fma_f32 v137, v137, v147, v121
	v_max_f32_e32 v136, 0, v136
	v_fma_f32 v141, -v133, v146, v141
	v_fma_f32 v138, v138, v147, v122
	v_fma_f32 v139, -v131, v146, v139
	v_mul_f32_e32 v148, v136, v136
	v_max_f32_e32 v136, 0, v137
	v_fma_f32 v140, v140, v147, v124
	v_fma_f32 v141, v141, v147, v125
	v_fma_f32 v142, -v134, v146, v142
	v_fma_f32 v143, -v135, v146, v143
	v_fma_f32 v139, v139, v147, v123
	v_mul_f32_e32 v149, v136, v136
	v_max_f32_e32 v136, 0, v138
	v_fma_f32 v96, -v112, v146, v96
	v_fma_f32 v142, v142, v147, v126
	v_fma_f32 v143, v143, v147, v127
	v_max_f32_e32 v140, 0, v140
	v_max_f32_e32 v141, 0, v141
	v_mul_f32_e32 v150, v136, v136
	v_max_f32_e32 v136, 0, v139
	v_fma_f32 v96, v96, v147, v100
	v_fma_f32 v97, -v113, v146, v97
	v_lshl_add_u64 v[144:145], v[174:175], 0, v[144:145]
	v_mul_f32_e32 v140, v140, v140
	v_mul_f32_e32 v141, v141, v141
	v_max_f32_e32 v142, 0, v142
	v_max_f32_e32 v143, 0, v143
	v_mul_f32_e32 v139, v136, v136
	v_cvt_pk_bf16_f32 v136, v140, v141
	v_fma_f32 v97, v97, v147, v101
	v_fma_f32 v98, -v114, v146, v98
	v_max_f32_e32 v96, 0, v96
	v_mul_f32_e32 v142, v142, v142
	v_mul_f32_e32 v143, v143, v143
	v_cvt_pk_bf16_f32 v137, v142, v143
	v_cvt_pk_bf16_f32 v138, v148, v149
	v_cvt_pk_bf16_f32 v139, v150, v139
	global_store_dwordx4 v[144:145], v[136:139], off nt
	v_fma_f32 v98, v98, v147, v102
	v_fma_f32 v99, -v115, v146, v99
	v_mul_f32_e32 v136, v96, v96
	v_max_f32_e32 v96, 0, v97
	v_fma_f32 v104, -v116, v146, v104
	v_fma_f32 v105, -v117, v146, v105
	v_fma_f32 v106, -v118, v146, v106
	v_fma_f32 v107, -v119, v146, v107
	v_fma_f32 v99, v99, v147, v103
	v_mul_f32_e32 v137, v96, v96
	v_max_f32_e32 v96, 0, v98
	v_fma_f32 v104, v104, v147, v108
	v_fma_f32 v105, v105, v147, v109
	v_fma_f32 v106, v106, v147, v110
	v_fma_f32 v107, v107, v147, v111
	v_mul_f32_e32 v138, v96, v96
	v_max_f32_e32 v96, 0, v99
	v_max_f32_e32 v104, 0, v104
	v_max_f32_e32 v105, 0, v105
	v_max_f32_e32 v106, 0, v106
	v_max_f32_e32 v107, 0, v107
	v_mul_f32_e32 v99, v96, v96
	v_mul_f32_e32 v104, v104, v104
	v_mul_f32_e32 v105, v105, v105
	v_mul_f32_e32 v106, v106, v106
	v_mul_f32_e32 v107, v107, v107
	v_cvt_pk_bf16_f32 v96, v104, v105
	v_cvt_pk_bf16_f32 v97, v106, v107
	v_cvt_pk_bf16_f32 v98, v136, v137
	v_cvt_pk_bf16_f32 v99, v138, v99
	global_store_dwordx4 v[144:145], v[96:99], off offset:256 nt
	s_nop 1
	v_pk_mul_f32 v[98:99], v[204:205], s[28:29] op_sel_hi:[1,0]
	v_lshlrev_b64 v[96:97], 14, v[202:203]
	v_fma_f32 v99, -v98, v98, v99
	v_max_f32_e32 v99, 0, v99
	v_add_f32_e32 v99, 0x3727c5ac, v99
	v_cmp_gt_f32_e32 vcc, s13, v99
	v_mul_f32_e32 v104, 0x4b800000, v99
	v_fma_f32 v88, -v128, v98, v88
	v_cndmask_b32_e32 v99, v99, v104, vcc
	v_rsq_f32_e32 v99, v99
	v_fma_f32 v89, -v129, v98, v89
	v_fma_f32 v90, -v130, v98, v90
	v_fma_f32 v92, -v132, v98, v92
	v_mul_f32_e32 v104, 0x45800000, v99
	v_cndmask_b32_e32 v99, v99, v104, vcc
	v_fma_f32 v88, v88, v99, v120
	v_fma_f32 v89, v89, v99, v121
	v_max_f32_e32 v88, 0, v88
	v_fma_f32 v93, -v133, v98, v93
	v_fma_f32 v90, v90, v99, v122
	v_fma_f32 v91, -v131, v98, v91
	v_mul_f32_e32 v104, v88, v88
	v_max_f32_e32 v88, 0, v89
	v_fma_f32 v92, v92, v99, v124
	v_fma_f32 v93, v93, v99, v125
	v_fma_f32 v94, -v134, v98, v94
	v_fma_f32 v95, -v135, v98, v95
	v_fma_f32 v91, v91, v99, v123
	v_mul_f32_e32 v105, v88, v88
	v_max_f32_e32 v88, 0, v90
	v_fma_f32 v80, -v112, v98, v80
	v_fma_f32 v94, v94, v99, v126
	v_fma_f32 v95, v95, v99, v127
	v_max_f32_e32 v92, 0, v92
	v_max_f32_e32 v93, 0, v93
	v_mul_f32_e32 v106, v88, v88
	v_max_f32_e32 v88, 0, v91
	v_fma_f32 v80, v80, v99, v100
	v_fma_f32 v81, -v113, v98, v81
	v_lshl_add_u64 v[96:97], v[174:175], 0, v[96:97]
	v_mul_f32_e32 v92, v92, v92
	v_mul_f32_e32 v93, v93, v93
	v_max_f32_e32 v94, 0, v94
	v_max_f32_e32 v95, 0, v95
	v_mul_f32_e32 v91, v88, v88
	v_cvt_pk_bf16_f32 v88, v92, v93
	v_fma_f32 v81, v81, v99, v101
	v_fma_f32 v82, -v114, v98, v82
	v_max_f32_e32 v80, 0, v80
	v_mul_f32_e32 v94, v94, v94
	v_mul_f32_e32 v95, v95, v95
	v_cvt_pk_bf16_f32 v89, v94, v95
	v_cvt_pk_bf16_f32 v90, v104, v105
	v_cvt_pk_bf16_f32 v91, v106, v91
	global_store_dwordx4 v[96:97], v[88:91], off nt
	v_fma_f32 v82, v82, v99, v102
	v_fma_f32 v83, -v115, v98, v83
	v_mul_f32_e32 v88, v80, v80
	v_max_f32_e32 v80, 0, v81
	v_fma_f32 v84, -v116, v98, v84
	v_fma_f32 v85, -v117, v98, v85
	v_fma_f32 v86, -v118, v98, v86
	v_fma_f32 v87, -v119, v98, v87
	v_fma_f32 v83, v83, v99, v103
	v_mul_f32_e32 v89, v80, v80
	v_max_f32_e32 v80, 0, v82
	v_fma_f32 v84, v84, v99, v108
	v_fma_f32 v85, v85, v99, v109
	v_fma_f32 v86, v86, v99, v110
	v_fma_f32 v87, v87, v99, v111
	v_mul_f32_e32 v90, v80, v80
	v_max_f32_e32 v80, 0, v83
	v_max_f32_e32 v84, 0, v84
	v_max_f32_e32 v85, 0, v85
	v_max_f32_e32 v86, 0, v86
	v_max_f32_e32 v87, 0, v87
	v_mul_f32_e32 v83, v80, v80
	v_mul_f32_e32 v84, v84, v84
	v_mul_f32_e32 v85, v85, v85
	v_mul_f32_e32 v86, v86, v86
	v_mul_f32_e32 v87, v87, v87
	v_cvt_pk_bf16_f32 v80, v84, v85
	v_cvt_pk_bf16_f32 v81, v86, v87
	v_cvt_pk_bf16_f32 v82, v88, v89
	v_cvt_pk_bf16_f32 v83, v90, v83
	global_store_dwordx4 v[96:97], v[80:83], off offset:256 nt
	s_nop 1
	v_pk_mul_f32 v[82:83], v[190:191], s[28:29] op_sel_hi:[1,0]
	v_lshlrev_b64 v[80:81], 14, v[188:189]
	v_fma_f32 v83, -v82, v82, v83
	v_max_f32_e32 v83, 0, v83
	v_add_f32_e32 v83, 0x3727c5ac, v83
	v_cmp_gt_f32_e32 vcc, s13, v83
	v_mul_f32_e32 v84, 0x4b800000, v83
	v_fma_f32 v72, -v128, v82, v72
	v_cndmask_b32_e32 v83, v83, v84, vcc
	v_rsq_f32_e32 v83, v83
	v_fma_f32 v73, -v129, v82, v73
	v_fma_f32 v74, -v130, v82, v74
	v_fma_f32 v76, -v132, v82, v76
	v_mul_f32_e32 v84, 0x45800000, v83
	v_cndmask_b32_e32 v83, v83, v84, vcc
	v_fma_f32 v72, v72, v83, v120
	v_fma_f32 v73, v73, v83, v121
	v_max_f32_e32 v72, 0, v72
	v_fma_f32 v77, -v133, v82, v77
	v_fma_f32 v74, v74, v83, v122
	v_fma_f32 v75, -v131, v82, v75
	v_mul_f32_e32 v84, v72, v72
	v_max_f32_e32 v72, 0, v73
	v_fma_f32 v76, v76, v83, v124
	v_fma_f32 v77, v77, v83, v125
	v_fma_f32 v78, -v134, v82, v78
	v_fma_f32 v79, -v135, v82, v79
	v_fma_f32 v75, v75, v83, v123
	v_mul_f32_e32 v85, v72, v72
	v_max_f32_e32 v72, 0, v74
	v_fma_f32 v64, -v112, v82, v64
	v_fma_f32 v78, v78, v83, v126
	v_fma_f32 v79, v79, v83, v127
	v_max_f32_e32 v76, 0, v76
	v_max_f32_e32 v77, 0, v77
	v_mul_f32_e32 v86, v72, v72
	v_max_f32_e32 v72, 0, v75
	v_fma_f32 v64, v64, v83, v100
	v_fma_f32 v65, -v113, v82, v65
	v_lshl_add_u64 v[80:81], v[174:175], 0, v[80:81]
	v_mul_f32_e32 v76, v76, v76
	v_mul_f32_e32 v77, v77, v77
	v_max_f32_e32 v78, 0, v78
	v_max_f32_e32 v79, 0, v79
	v_mul_f32_e32 v75, v72, v72
	v_cvt_pk_bf16_f32 v72, v76, v77
	v_fma_f32 v65, v65, v83, v101
	v_fma_f32 v66, -v114, v82, v66
	v_max_f32_e32 v64, 0, v64
	v_mul_f32_e32 v78, v78, v78
	v_mul_f32_e32 v79, v79, v79
	v_cvt_pk_bf16_f32 v73, v78, v79
	v_cvt_pk_bf16_f32 v74, v84, v85
	v_cvt_pk_bf16_f32 v75, v86, v75
	global_store_dwordx4 v[80:81], v[72:75], off nt
	v_fma_f32 v66, v66, v83, v102
	v_fma_f32 v67, -v115, v82, v67
	v_mul_f32_e32 v72, v64, v64
	v_max_f32_e32 v64, 0, v65
	v_fma_f32 v68, -v116, v82, v68
	v_fma_f32 v69, -v117, v82, v69
	v_fma_f32 v70, -v118, v82, v70
	v_fma_f32 v71, -v119, v82, v71
	v_fma_f32 v67, v67, v83, v103
	v_mul_f32_e32 v73, v64, v64
	v_max_f32_e32 v64, 0, v66
	v_fma_f32 v68, v68, v83, v108
	v_fma_f32 v69, v69, v83, v109
	v_fma_f32 v70, v70, v83, v110
	v_fma_f32 v71, v71, v83, v111
	v_mul_f32_e32 v74, v64, v64
	v_max_f32_e32 v64, 0, v67
	v_max_f32_e32 v68, 0, v68
	v_max_f32_e32 v69, 0, v69
	v_max_f32_e32 v70, 0, v70
	v_max_f32_e32 v71, 0, v71
	v_mul_f32_e32 v67, v64, v64
	v_mul_f32_e32 v68, v68, v68
	v_mul_f32_e32 v69, v69, v69
	v_mul_f32_e32 v70, v70, v70
	v_mul_f32_e32 v71, v71, v71
	v_cvt_pk_bf16_f32 v64, v68, v69
	v_cvt_pk_bf16_f32 v65, v70, v71
	v_cvt_pk_bf16_f32 v66, v72, v73
	v_cvt_pk_bf16_f32 v67, v74, v67
	global_store_dwordx4 v[80:81], v[64:67], off offset:256 nt
	s_nop 1
	v_pk_mul_f32 v[66:67], v[186:187], s[28:29] op_sel_hi:[1,0]
	v_lshlrev_b64 v[64:65], 14, v[184:185]
	v_fma_f32 v67, -v66, v66, v67
	v_max_f32_e32 v67, 0, v67
	v_add_f32_e32 v67, 0x3727c5ac, v67
	v_cmp_gt_f32_e32 vcc, s13, v67
	v_mul_f32_e32 v68, 0x4b800000, v67
	v_fma_f32 v56, -v128, v66, v56
	v_cndmask_b32_e32 v67, v67, v68, vcc
	v_rsq_f32_e32 v67, v67
	v_fma_f32 v57, -v129, v66, v57
	v_fma_f32 v58, -v130, v66, v58
	v_fma_f32 v60, -v132, v66, v60
	v_mul_f32_e32 v68, 0x45800000, v67
	v_cndmask_b32_e32 v67, v67, v68, vcc
	v_fma_f32 v56, v56, v67, v120
	v_fma_f32 v57, v57, v67, v121
	v_max_f32_e32 v56, 0, v56
	v_fma_f32 v61, -v133, v66, v61
	v_fma_f32 v58, v58, v67, v122
	v_fma_f32 v59, -v131, v66, v59
	v_mul_f32_e32 v68, v56, v56
	v_max_f32_e32 v56, 0, v57
	v_fma_f32 v60, v60, v67, v124
	v_fma_f32 v61, v61, v67, v125
	v_fma_f32 v62, -v134, v66, v62
	v_fma_f32 v63, -v135, v66, v63
	v_fma_f32 v59, v59, v67, v123
	v_mul_f32_e32 v69, v56, v56
	v_max_f32_e32 v56, 0, v58
	v_fma_f32 v48, -v112, v66, v48
	v_fma_f32 v62, v62, v67, v126
	v_fma_f32 v63, v63, v67, v127
	v_max_f32_e32 v60, 0, v60
	v_max_f32_e32 v61, 0, v61
	v_mul_f32_e32 v70, v56, v56
	v_max_f32_e32 v56, 0, v59
	v_fma_f32 v48, v48, v67, v100
	v_fma_f32 v49, -v113, v66, v49
	v_lshl_add_u64 v[64:65], v[174:175], 0, v[64:65]
	v_mul_f32_e32 v60, v60, v60
	v_mul_f32_e32 v61, v61, v61
	v_max_f32_e32 v62, 0, v62
	v_max_f32_e32 v63, 0, v63
	v_mul_f32_e32 v59, v56, v56
	v_cvt_pk_bf16_f32 v56, v60, v61
	v_fma_f32 v49, v49, v67, v101
	v_fma_f32 v50, -v114, v66, v50
	v_max_f32_e32 v48, 0, v48
	v_mul_f32_e32 v62, v62, v62
	v_mul_f32_e32 v63, v63, v63
	v_cvt_pk_bf16_f32 v57, v62, v63
	v_cvt_pk_bf16_f32 v58, v68, v69
	v_cvt_pk_bf16_f32 v59, v70, v59
	global_store_dwordx4 v[64:65], v[56:59], off nt
	v_fma_f32 v50, v50, v67, v102
	v_fma_f32 v51, -v115, v66, v51
	v_mul_f32_e32 v56, v48, v48
	v_max_f32_e32 v48, 0, v49
	v_fma_f32 v52, -v116, v66, v52
	v_fma_f32 v53, -v117, v66, v53
	v_fma_f32 v54, -v118, v66, v54
	v_fma_f32 v55, -v119, v66, v55
	v_fma_f32 v51, v51, v67, v103
	v_mul_f32_e32 v57, v48, v48
	v_max_f32_e32 v48, 0, v50
	v_fma_f32 v52, v52, v67, v108
	v_fma_f32 v53, v53, v67, v109
	v_fma_f32 v54, v54, v67, v110
	v_fma_f32 v55, v55, v67, v111
	v_mul_f32_e32 v58, v48, v48
	v_max_f32_e32 v48, 0, v51
	v_max_f32_e32 v52, 0, v52
	v_max_f32_e32 v53, 0, v53
	v_max_f32_e32 v54, 0, v54
	v_max_f32_e32 v55, 0, v55
	v_mul_f32_e32 v51, v48, v48
	v_mul_f32_e32 v52, v52, v52
	v_mul_f32_e32 v53, v53, v53
	v_mul_f32_e32 v54, v54, v54
	v_mul_f32_e32 v55, v55, v55
	v_cvt_pk_bf16_f32 v48, v52, v53
	v_cvt_pk_bf16_f32 v49, v54, v55
	v_cvt_pk_bf16_f32 v50, v56, v57
	v_cvt_pk_bf16_f32 v51, v58, v51
	global_store_dwordx4 v[64:65], v[48:51], off offset:256 nt
	s_nop 1
	v_pk_mul_f32 v[50:51], v[182:183], s[28:29] op_sel_hi:[1,0]
	v_lshlrev_b64 v[48:49], 14, v[180:181]
	v_fma_f32 v51, -v50, v50, v51
	v_max_f32_e32 v51, 0, v51
	v_add_f32_e32 v51, 0x3727c5ac, v51
	v_cmp_gt_f32_e32 vcc, s13, v51
	v_mul_f32_e32 v52, 0x4b800000, v51
	v_fma_f32 v40, -v128, v50, v40
	v_cndmask_b32_e32 v51, v51, v52, vcc
	v_rsq_f32_e32 v51, v51
	v_fma_f32 v41, -v129, v50, v41
	v_fma_f32 v42, -v130, v50, v42
	v_fma_f32 v44, -v132, v50, v44
	v_mul_f32_e32 v52, 0x45800000, v51
	v_cndmask_b32_e32 v51, v51, v52, vcc
	v_fma_f32 v40, v40, v51, v120
	v_fma_f32 v41, v41, v51, v121
	v_max_f32_e32 v40, 0, v40
	v_fma_f32 v45, -v133, v50, v45
	v_fma_f32 v42, v42, v51, v122
	v_fma_f32 v43, -v131, v50, v43
	v_mul_f32_e32 v52, v40, v40
	v_max_f32_e32 v40, 0, v41
	v_fma_f32 v44, v44, v51, v124
	v_fma_f32 v45, v45, v51, v125
	v_fma_f32 v46, -v134, v50, v46
	v_fma_f32 v47, -v135, v50, v47
	v_fma_f32 v43, v43, v51, v123
	v_mul_f32_e32 v53, v40, v40
	v_max_f32_e32 v40, 0, v42
	v_fma_f32 v32, -v112, v50, v32
	v_fma_f32 v46, v46, v51, v126
	v_fma_f32 v47, v47, v51, v127
	v_max_f32_e32 v44, 0, v44
	v_max_f32_e32 v45, 0, v45
	v_mul_f32_e32 v54, v40, v40
	v_max_f32_e32 v40, 0, v43
	v_fma_f32 v32, v32, v51, v100
	v_fma_f32 v33, -v113, v50, v33
	v_lshl_add_u64 v[48:49], v[174:175], 0, v[48:49]
	v_mul_f32_e32 v44, v44, v44
	v_mul_f32_e32 v45, v45, v45
	v_max_f32_e32 v46, 0, v46
	v_max_f32_e32 v47, 0, v47
	v_mul_f32_e32 v43, v40, v40
	v_cvt_pk_bf16_f32 v40, v44, v45
	v_fma_f32 v33, v33, v51, v101
	v_fma_f32 v34, -v114, v50, v34
	v_max_f32_e32 v32, 0, v32
	v_mul_f32_e32 v46, v46, v46
	v_mul_f32_e32 v47, v47, v47
	v_cvt_pk_bf16_f32 v41, v46, v47
	v_cvt_pk_bf16_f32 v42, v52, v53
	v_cvt_pk_bf16_f32 v43, v54, v43
	global_store_dwordx4 v[48:49], v[40:43], off nt
	v_fma_f32 v34, v34, v51, v102
	v_fma_f32 v35, -v115, v50, v35
	v_mul_f32_e32 v40, v32, v32
	v_max_f32_e32 v32, 0, v33
	v_fma_f32 v36, -v116, v50, v36
	v_fma_f32 v37, -v117, v50, v37
	v_fma_f32 v38, -v118, v50, v38
	v_fma_f32 v39, -v119, v50, v39
	v_fma_f32 v35, v35, v51, v103
	v_mul_f32_e32 v41, v32, v32
	v_max_f32_e32 v32, 0, v34
	v_fma_f32 v36, v36, v51, v108
	v_fma_f32 v37, v37, v51, v109
	v_fma_f32 v38, v38, v51, v110
	v_fma_f32 v39, v39, v51, v111
	v_mul_f32_e32 v42, v32, v32
	v_max_f32_e32 v32, 0, v35
	v_max_f32_e32 v36, 0, v36
	v_max_f32_e32 v37, 0, v37
	v_max_f32_e32 v38, 0, v38
	v_max_f32_e32 v39, 0, v39
	v_mul_f32_e32 v35, v32, v32
	v_mul_f32_e32 v36, v36, v36
	v_mul_f32_e32 v37, v37, v37
	v_mul_f32_e32 v38, v38, v38
	v_mul_f32_e32 v39, v39, v39
	v_cvt_pk_bf16_f32 v32, v36, v37
	v_cvt_pk_bf16_f32 v33, v38, v39
	v_cvt_pk_bf16_f32 v34, v40, v41
	v_cvt_pk_bf16_f32 v35, v42, v35
	global_store_dwordx4 v[48:49], v[32:35], off offset:256 nt
	s_nop 1
	v_pk_mul_f32 v[34:35], v[176:177], s[28:29] op_sel_hi:[1,0]
	v_lshlrev_b64 v[32:33], 14, v[178:179]
	v_fma_f32 v35, -v34, v34, v35
	v_max_f32_e32 v35, 0, v35
	v_add_f32_e32 v35, 0x3727c5ac, v35
	v_cmp_gt_f32_e32 vcc, s13, v35
	v_mul_f32_e32 v36, 0x4b800000, v35
	v_fma_f32 v24, -v128, v34, v24
	v_cndmask_b32_e32 v35, v35, v36, vcc
	v_rsq_f32_e32 v35, v35
	v_fma_f32 v25, -v129, v34, v25
	v_fma_f32 v26, -v130, v34, v26
	v_fma_f32 v28, -v132, v34, v28
	v_mul_f32_e32 v36, 0x45800000, v35
	v_cndmask_b32_e32 v35, v35, v36, vcc
	v_fma_f32 v24, v24, v35, v120
	v_fma_f32 v25, v25, v35, v121
	v_max_f32_e32 v24, 0, v24
	v_fma_f32 v29, -v133, v34, v29
	v_fma_f32 v26, v26, v35, v122
	v_fma_f32 v27, -v131, v34, v27
	v_mul_f32_e32 v36, v24, v24
	v_max_f32_e32 v24, 0, v25
	v_fma_f32 v28, v28, v35, v124
	v_fma_f32 v29, v29, v35, v125
	v_fma_f32 v30, -v134, v34, v30
	v_fma_f32 v31, -v135, v34, v31
	v_fma_f32 v27, v27, v35, v123
	v_mul_f32_e32 v37, v24, v24
	v_max_f32_e32 v24, 0, v26
	v_fma_f32 v16, -v112, v34, v16
	v_fma_f32 v30, v30, v35, v126
	v_fma_f32 v31, v31, v35, v127
	v_max_f32_e32 v28, 0, v28
	v_max_f32_e32 v29, 0, v29
	v_mul_f32_e32 v38, v24, v24
	v_max_f32_e32 v24, 0, v27
	v_fma_f32 v16, v16, v35, v100
	v_fma_f32 v17, -v113, v34, v17
	v_lshl_add_u64 v[32:33], v[174:175], 0, v[32:33]
	v_mul_f32_e32 v28, v28, v28
	v_mul_f32_e32 v29, v29, v29
	v_max_f32_e32 v30, 0, v30
	v_max_f32_e32 v31, 0, v31
	v_mul_f32_e32 v27, v24, v24
	v_cvt_pk_bf16_f32 v24, v28, v29
	v_fma_f32 v17, v17, v35, v101
	v_fma_f32 v18, -v114, v34, v18
	v_max_f32_e32 v16, 0, v16
	v_mul_f32_e32 v30, v30, v30
	v_mul_f32_e32 v31, v31, v31
	v_cvt_pk_bf16_f32 v25, v30, v31
	v_cvt_pk_bf16_f32 v26, v36, v37
	v_cvt_pk_bf16_f32 v27, v38, v27
	global_store_dwordx4 v[32:33], v[24:27], off nt
	v_fma_f32 v18, v18, v35, v102
	v_fma_f32 v19, -v115, v34, v19
	v_mul_f32_e32 v24, v16, v16
	v_max_f32_e32 v16, 0, v17
	v_fma_f32 v20, -v116, v34, v20
	v_fma_f32 v21, -v117, v34, v21
	v_fma_f32 v22, -v118, v34, v22
	v_fma_f32 v23, -v119, v34, v23
	v_fma_f32 v19, v19, v35, v103
	v_mul_f32_e32 v25, v16, v16
	v_max_f32_e32 v16, 0, v18
	v_fma_f32 v20, v20, v35, v108
	v_fma_f32 v21, v21, v35, v109
	v_fma_f32 v22, v22, v35, v110
	v_fma_f32 v23, v23, v35, v111
	v_mul_f32_e32 v26, v16, v16
	v_max_f32_e32 v16, 0, v19
	v_max_f32_e32 v20, 0, v20
	v_max_f32_e32 v21, 0, v21
	v_max_f32_e32 v22, 0, v22
	v_max_f32_e32 v23, 0, v23
	v_mul_f32_e32 v19, v16, v16
	v_mul_f32_e32 v20, v20, v20
	v_mul_f32_e32 v21, v21, v21
	v_mul_f32_e32 v22, v22, v22
	v_mul_f32_e32 v23, v23, v23
	v_cvt_pk_bf16_f32 v16, v20, v21
	v_cvt_pk_bf16_f32 v17, v22, v23
	v_cvt_pk_bf16_f32 v18, v24, v25
	v_cvt_pk_bf16_f32 v19, v26, v19
	global_store_dwordx4 v[32:33], v[16:19], off offset:256 nt
	s_nop 1
	v_pk_mul_f32 v[18:19], v[170:171], s[28:29] op_sel_hi:[1,0]
	v_lshlrev_b64 v[16:17], 14, v[172:173]
	v_fma_f32 v19, -v18, v18, v19
	v_max_f32_e32 v19, 0, v19
	v_add_f32_e32 v19, 0x3727c5ac, v19
	v_cmp_gt_f32_e32 vcc, s13, v19
	v_mul_f32_e32 v20, 0x4b800000, v19
	v_fma_f32 v8, -v128, v18, v8
	v_cndmask_b32_e32 v19, v19, v20, vcc
	v_rsq_f32_e32 v19, v19
	v_fma_f32 v9, -v129, v18, v9
	v_fma_f32 v15, -v135, v18, v15
	v_fma_f32 v10, -v130, v18, v10
	v_mul_f32_e32 v20, 0x45800000, v19
	v_cndmask_b32_e32 v19, v19, v20, vcc
	v_fma_f32 v8, v8, v19, v120
	v_fma_f32 v9, v9, v19, v121
	v_max_f32_e32 v8, 0, v8
	v_fma_f32 v12, -v132, v18, v12
	v_fma_f32 v13, -v133, v18, v13
	v_fmac_f32_e32 v127, v15, v19
	v_fma_f32 v10, v10, v19, v122
	v_fma_f32 v11, -v131, v18, v11
	v_mul_f32_e32 v15, v8, v8
	v_max_f32_e32 v8, 0, v9
	v_fma_f32 v0, -v112, v18, v0
	v_fma_f32 v12, v12, v19, v124
	v_fma_f32 v13, v13, v19, v125
	v_fma_f32 v14, -v134, v18, v14
	v_fmac_f32_e32 v123, v11, v19
	v_mul_f32_e32 v20, v8, v8
	v_max_f32_e32 v8, 0, v10
	v_fma_f32 v0, v0, v19, v100
	v_fma_f32 v1, -v113, v18, v1
	v_fma_f32 v14, v14, v19, v126
	v_max_f32_e32 v11, 0, v12
	v_max_f32_e32 v12, 0, v13
	v_mul_f32_e32 v21, v8, v8
	v_max_f32_e32 v8, 0, v123
	v_fma_f32 v4, -v116, v18, v4
	v_fma_f32 v7, -v119, v18, v7
	v_fma_f32 v1, v1, v19, v101
	v_fma_f32 v2, -v114, v18, v2
	v_max_f32_e32 v0, 0, v0
	v_lshl_add_u64 v[16:17], v[174:175], 0, v[16:17]
	v_mul_f32_e32 v11, v11, v11
	v_mul_f32_e32 v12, v12, v12
	v_max_f32_e32 v13, 0, v14
	v_max_f32_e32 v14, 0, v127
	v_mul_f32_e32 v22, v8, v8
	v_cvt_pk_bf16_f32 v8, v11, v12
	v_fma_f32 v4, v4, v19, v108
	v_fma_f32 v5, -v117, v18, v5
	v_fma_f32 v6, -v118, v18, v6
	v_fmac_f32_e32 v111, v7, v19
	v_fma_f32 v2, v2, v19, v102
	v_fma_f32 v3, -v115, v18, v3
	v_mul_f32_e32 v7, v0, v0
	v_max_f32_e32 v0, 0, v1
	v_mul_f32_e32 v13, v13, v13
	v_mul_f32_e32 v14, v14, v14
	v_cvt_pk_bf16_f32 v9, v13, v14
	v_cvt_pk_bf16_f32 v10, v15, v20
	v_cvt_pk_bf16_f32 v11, v21, v22
	global_store_dwordx4 v[16:17], v[8:11], off nt
	v_fma_f32 v5, v5, v19, v109
	v_fma_f32 v6, v6, v19, v110
	v_fmac_f32_e32 v103, v3, v19
	v_max_f32_e32 v3, 0, v4
	v_mul_f32_e32 v8, v0, v0
	v_max_f32_e32 v0, 0, v2
	v_mul_f32_e32 v3, v3, v3
	v_max_f32_e32 v4, 0, v5
	v_max_f32_e32 v5, 0, v6
	v_max_f32_e32 v6, 0, v111
	v_mul_f32_e32 v9, v0, v0
	v_max_f32_e32 v0, 0, v103
	s_and_b64 vcc, exec, s[38:39]
	v_mul_f32_e32 v4, v4, v4
	v_mul_f32_e32 v5, v5, v5
	v_mul_f32_e32 v6, v6, v6
	v_mul_f32_e32 v10, v0, v0
	v_cvt_pk_bf16_f32 v0, v3, v4
	v_cvt_pk_bf16_f32 v1, v5, v6
	v_cvt_pk_bf16_f32 v2, v7, v8
	v_cvt_pk_bf16_f32 v3, v9, v10
	global_store_dwordx4 v[16:17], v[0:3], off offset:256 nt
	s_cbranch_vccz .LBB0_1084
	s_waitcnt vmcnt(0)
	s_cmpk_gt_u32 s6, 0xff
	s_cbranch_scc1 .LBB0_1095
	s_barrier
